# modnorm: forget-gate weight staging with 16 rows x 64 contiguous bytes per load instruction and all 16 loads in flight (was one row per lane: 64 cache lines per instruction)
# baseline (speedup 1.0000x reference)
.LBB0_296:
	s_movk_i32 s0, 0x800
	s_ashr_i32 s95, s94, 31
	v_cmp_gt_i32_e32 vcc, s0, v200
	s_and_saveexec_b64 s[0:1], vcc
	v_readlane_b32 s8, v253, 35
	v_readlane_b32 s9, v253, 36
	s_cbranch_execz .LBB0_299
	s_mul_i32 s2, s94, 0x3820000
	v_readlane_b32 s4, v253, 13
	s_mul_hi_i32 s3, s94, 0x3820000
	s_add_u32 s2, s4, s2
	v_readlane_b32 s4, v253, 30
	s_addc_u32 s3, s4, s3
	v_mov_b64_e32 v[0:1], s[2:3]
	v_lshrrev_b32_e32 v2, 2, v200
	v_and_b32_e32 v3, 3, v200
	s_movk_i32 s2, 0x7040
	v_mad_i64_i32 v[0:1], s[2:3], v2, s2, v[0:1]
	v_lshlrev_b32_e32 v4, 4, v3
	v_mov_b32_e32 v5, 0
	v_lshl_add_u64 v[0:1], v[0:1], 0, v[4:5]
	s_mov_b32 s2, 0x382000
	s_mov_b32 s3, 0
	global_load_dwordx4 v[32:35], v[0:1], off
	v_lshl_add_u64 v[0:1], v[0:1], 0, s[2:3]
	global_load_dwordx4 v[36:39], v[0:1], off
	v_lshl_add_u64 v[0:1], v[0:1], 0, s[2:3]
	global_load_dwordx4 v[40:43], v[0:1], off
	v_lshl_add_u64 v[0:1], v[0:1], 0, s[2:3]
	global_load_dwordx4 v[44:47], v[0:1], off
	v_lshl_add_u64 v[0:1], v[0:1], 0, s[2:3]
	global_load_dwordx4 v[48:51], v[0:1], off
	v_lshl_add_u64 v[0:1], v[0:1], 0, s[2:3]
	global_load_dwordx4 v[52:55], v[0:1], off
	v_lshl_add_u64 v[0:1], v[0:1], 0, s[2:3]
	global_load_dwordx4 v[56:59], v[0:1], off
	v_lshl_add_u64 v[0:1], v[0:1], 0, s[2:3]
	global_load_dwordx4 v[60:63], v[0:1], off
	v_lshl_add_u64 v[0:1], v[0:1], 0, s[2:3]
	global_load_dwordx4 v[64:67], v[0:1], off
	v_lshl_add_u64 v[0:1], v[0:1], 0, s[2:3]
	global_load_dwordx4 v[68:71], v[0:1], off
	v_lshl_add_u64 v[0:1], v[0:1], 0, s[2:3]
	global_load_dwordx4 v[72:75], v[0:1], off
	v_lshl_add_u64 v[0:1], v[0:1], 0, s[2:3]
	global_load_dwordx4 v[76:79], v[0:1], off
	v_lshl_add_u64 v[0:1], v[0:1], 0, s[2:3]
	global_load_dwordx4 v[80:83], v[0:1], off
	v_lshl_add_u64 v[0:1], v[0:1], 0, s[2:3]
	global_load_dwordx4 v[84:87], v[0:1], off
	v_lshl_add_u64 v[0:1], v[0:1], 0, s[2:3]
	global_load_dwordx4 v[88:91], v[0:1], off
	v_lshl_add_u64 v[0:1], v[0:1], 0, s[2:3]
	global_load_dwordx4 v[92:95], v[0:1], off
	v_lshrrev_b32_e32 v6, 3, v2
	v_and_b32_e32 v7, 7, v2
	v_lshlrev_b32_e32 v7, 1, v7
	v_lshlrev_b32_e32 v8, 2, v3
	v_add_u32_e32 v9, 0, v8
	v_xor_b32_e32 v10, v6, v9
	v_lshlrev_b32_e32 v10, 4, v10
	v_lshl_add_u32 v10, v9, 12, v10
	v_add_u32_e32 v20, v10, v7
	v_add_u32_e32 v9, 1, v8
	v_xor_b32_e32 v10, v6, v9
	v_lshlrev_b32_e32 v10, 4, v10
	v_lshl_add_u32 v10, v9, 12, v10
	v_add_u32_e32 v21, v10, v7
	v_add_u32_e32 v9, 2, v8
	v_xor_b32_e32 v10, v6, v9
	v_lshlrev_b32_e32 v10, 4, v10
	v_lshl_add_u32 v10, v9, 12, v10
	v_add_u32_e32 v22, v10, v7
	v_add_u32_e32 v9, 3, v8
	v_xor_b32_e32 v10, v6, v9
	v_lshlrev_b32_e32 v10, 4, v10
	v_lshl_add_u32 v10, v9, 12, v10
	v_add_u32_e32 v23, v10, v7
	s_waitcnt vmcnt(15)
	v_cvt_pk_bf16_f32 v32, v32, v32
	v_cvt_pk_bf16_f32 v33, v33, v33
	v_cvt_pk_bf16_f32 v34, v34, v34
	v_cvt_pk_bf16_f32 v35, v35, v35
	ds_write_b16 v20, v32 offset:16384
	ds_write_b16 v21, v33 offset:16384
	ds_write_b16 v22, v34 offset:16384
	ds_write_b16 v23, v35 offset:16384
	s_waitcnt vmcnt(14)
	v_cvt_pk_bf16_f32 v36, v36, v36
	v_cvt_pk_bf16_f32 v37, v37, v37
	v_cvt_pk_bf16_f32 v38, v38, v38
	v_cvt_pk_bf16_f32 v39, v39, v39
	ds_write_b16 v20, v36 offset:16640
	ds_write_b16 v21, v37 offset:16640
	ds_write_b16 v22, v38 offset:16640
	ds_write_b16 v23, v39 offset:16640
	s_waitcnt vmcnt(13)
	v_cvt_pk_bf16_f32 v40, v40, v40
	v_cvt_pk_bf16_f32 v41, v41, v41
	v_cvt_pk_bf16_f32 v42, v42, v42
	v_cvt_pk_bf16_f32 v43, v43, v43
	ds_write_b16 v20, v40 offset:16896
	ds_write_b16 v21, v41 offset:16896
	ds_write_b16 v22, v42 offset:16896
	ds_write_b16 v23, v43 offset:16896
	s_waitcnt vmcnt(12)
	v_cvt_pk_bf16_f32 v44, v44, v44
	v_cvt_pk_bf16_f32 v45, v45, v45
	v_cvt_pk_bf16_f32 v46, v46, v46
	v_cvt_pk_bf16_f32 v47, v47, v47
	ds_write_b16 v20, v44 offset:17152
	ds_write_b16 v21, v45 offset:17152
	ds_write_b16 v22, v46 offset:17152
	ds_write_b16 v23, v47 offset:17152
	s_waitcnt vmcnt(11)
	v_cvt_pk_bf16_f32 v48, v48, v48
	v_cvt_pk_bf16_f32 v49, v49, v49
	v_cvt_pk_bf16_f32 v50, v50, v50
	v_cvt_pk_bf16_f32 v51, v51, v51
	ds_write_b16 v20, v48 offset:17408
	ds_write_b16 v21, v49 offset:17408
	ds_write_b16 v22, v50 offset:17408
	ds_write_b16 v23, v51 offset:17408
	s_waitcnt vmcnt(10)
	v_cvt_pk_bf16_f32 v52, v52, v52
	v_cvt_pk_bf16_f32 v53, v53, v53
	v_cvt_pk_bf16_f32 v54, v54, v54
	v_cvt_pk_bf16_f32 v55, v55, v55
	ds_write_b16 v20, v52 offset:17664
	ds_write_b16 v21, v53 offset:17664
	ds_write_b16 v22, v54 offset:17664
	ds_write_b16 v23, v55 offset:17664
	s_waitcnt vmcnt(9)
	v_cvt_pk_bf16_f32 v56, v56, v56
	v_cvt_pk_bf16_f32 v57, v57, v57
	v_cvt_pk_bf16_f32 v58, v58, v58
	v_cvt_pk_bf16_f32 v59, v59, v59
	ds_write_b16 v20, v56 offset:17920
	ds_write_b16 v21, v57 offset:17920
	ds_write_b16 v22, v58 offset:17920
	ds_write_b16 v23, v59 offset:17920
	s_waitcnt vmcnt(8)
	v_cvt_pk_bf16_f32 v60, v60, v60
	v_cvt_pk_bf16_f32 v61, v61, v61
	v_cvt_pk_bf16_f32 v62, v62, v62
	v_cvt_pk_bf16_f32 v63, v63, v63
	ds_write_b16 v20, v60 offset:18176
	ds_write_b16 v21, v61 offset:18176
	ds_write_b16 v22, v62 offset:18176
	ds_write_b16 v23, v63 offset:18176
	s_waitcnt vmcnt(7)
	v_cvt_pk_bf16_f32 v64, v64, v64
	v_cvt_pk_bf16_f32 v65, v65, v65
	v_cvt_pk_bf16_f32 v66, v66, v66
	v_cvt_pk_bf16_f32 v67, v67, v67
	ds_write_b16 v20, v64 offset:18432
	ds_write_b16 v21, v65 offset:18432
	ds_write_b16 v22, v66 offset:18432
	ds_write_b16 v23, v67 offset:18432
	s_waitcnt vmcnt(6)
	v_cvt_pk_bf16_f32 v68, v68, v68
	v_cvt_pk_bf16_f32 v69, v69, v69
	v_cvt_pk_bf16_f32 v70, v70, v70
	v_cvt_pk_bf16_f32 v71, v71, v71
	ds_write_b16 v20, v68 offset:18688
	ds_write_b16 v21, v69 offset:18688
	ds_write_b16 v22, v70 offset:18688
	ds_write_b16 v23, v71 offset:18688
	s_waitcnt vmcnt(5)
	v_cvt_pk_bf16_f32 v72, v72, v72
	v_cvt_pk_bf16_f32 v73, v73, v73
	v_cvt_pk_bf16_f32 v74, v74, v74
	v_cvt_pk_bf16_f32 v75, v75, v75
	ds_write_b16 v20, v72 offset:18944
	ds_write_b16 v21, v73 offset:18944
	ds_write_b16 v22, v74 offset:18944
	ds_write_b16 v23, v75 offset:18944
	s_waitcnt vmcnt(4)
	v_cvt_pk_bf16_f32 v76, v76, v76
	v_cvt_pk_bf16_f32 v77, v77, v77
	v_cvt_pk_bf16_f32 v78, v78, v78
	v_cvt_pk_bf16_f32 v79, v79, v79
	ds_write_b16 v20, v76 offset:19200
	ds_write_b16 v21, v77 offset:19200
	ds_write_b16 v22, v78 offset:19200
	ds_write_b16 v23, v79 offset:19200
	s_waitcnt vmcnt(3)
	v_cvt_pk_bf16_f32 v80, v80, v80
	v_cvt_pk_bf16_f32 v81, v81, v81
	v_cvt_pk_bf16_f32 v82, v82, v82
	v_cvt_pk_bf16_f32 v83, v83, v83
	ds_write_b16 v20, v80 offset:19456
	ds_write_b16 v21, v81 offset:19456
	ds_write_b16 v22, v82 offset:19456
	ds_write_b16 v23, v83 offset:19456
	s_waitcnt vmcnt(2)
	v_cvt_pk_bf16_f32 v84, v84, v84
	v_cvt_pk_bf16_f32 v85, v85, v85
	v_cvt_pk_bf16_f32 v86, v86, v86
	v_cvt_pk_bf16_f32 v87, v87, v87
	ds_write_b16 v20, v84 offset:19712
	ds_write_b16 v21, v85 offset:19712
	ds_write_b16 v22, v86 offset:19712
	ds_write_b16 v23, v87 offset:19712
	s_waitcnt vmcnt(1)
	v_cvt_pk_bf16_f32 v88, v88, v88
	v_cvt_pk_bf16_f32 v89, v89, v89
	v_cvt_pk_bf16_f32 v90, v90, v90
	v_cvt_pk_bf16_f32 v91, v91, v91
	ds_write_b16 v20, v88 offset:19968
	ds_write_b16 v21, v89 offset:19968
	ds_write_b16 v22, v90 offset:19968
	ds_write_b16 v23, v91 offset:19968
	s_waitcnt vmcnt(0)
	v_cvt_pk_bf16_f32 v92, v92, v92
	v_cvt_pk_bf16_f32 v93, v93, v93
	v_cvt_pk_bf16_f32 v94, v94, v94
	v_cvt_pk_bf16_f32 v95, v95, v95
	ds_write_b16 v20, v92 offset:20224
	ds_write_b16 v21, v93 offset:20224
	ds_write_b16 v22, v94 offset:20224
	ds_write_b16 v23, v95 offset:20224
	s_waitcnt lgkmcnt(0)
